# final RMSNorm: gain vector loaded once before the row loop (was four dependent loads with full waits per row)
# speedup vs baseline: 1.0043x; 1.0043x over previous
.LBB0_926:
	v_readlane_b32 s0, v251, 1
	v_readlane_b32 s1, v251, 2
	s_mov_b64 s[4:5], s[0:1]
	s_cmp_ge_i32 s44, s4
	v_readlane_b32 s2, v251, 3
	v_readlane_b32 s3, v251, 4
	s_cselect_b64 s[0:1], -1, 0
	s_cmp_lt_i32 s44, s5
	s_cselect_b64 s[2:3], -1, 0
	s_and_b64 s[0:1], s[0:1], s[2:3]
	s_and_b64 vcc, exec, s[0:1]
	s_cbranch_vccz .LBB0_930
	v_readlane_b32 s1, v251, 0
	v_readfirstlane_b32 s0, v199
	s_ashr_i32 s0, s0, 6
	s_lshl_b32 s1, s1, 3
	s_add_i32 s4, s0, s1
	s_cmpk_gt_i32 s4, 0x3fff
	s_cbranch_scc1 .LBB0_930
	v_and_b32_e32 v0, 64, v222
	v_add_u32_e32 v2, 64, v0
	v_xor_b32_e32 v3, 1, v222
	v_cmp_lt_i32_e32 vcc, v3, v2
	v_readlane_b32 s2, v251, 7
	v_readlane_b32 s3, v251, 8
	v_cndmask_b32_e32 v3, v222, v3, vcc
	v_lshlrev_b32_e32 v6, 2, v3
	v_xor_b32_e32 v3, 2, v222
	v_cmp_lt_i32_e32 vcc, v3, v2
	s_load_dwordx4 s[8:11], s[2:3], 0xb8
	s_ashr_i32 s3, s0, 31
	v_cndmask_b32_e32 v3, v222, v3, vcc
	v_lshlrev_b32_e32 v7, 2, v3
	v_xor_b32_e32 v3, 4, v222
	v_cmp_lt_i32_e32 vcc, v3, v2
	s_ashr_i32 s5, s1, 31
	s_add_u32 s2, s0, s1
	v_cndmask_b32_e32 v3, v222, v3, vcc
	v_lshlrev_b32_e32 v8, 2, v3
	v_xor_b32_e32 v3, 8, v222
	v_cmp_lt_i32_e32 vcc, v3, v2
	s_addc_u32 s3, s3, s5
	s_lshl_b64 s[0:1], s[2:3], 12
	v_cndmask_b32_e32 v3, v222, v3, vcc
	v_lshlrev_b32_e32 v9, 2, v3
	v_xor_b32_e32 v3, 16, v222
	v_cmp_lt_i32_e32 vcc, v3, v2
	v_and_b32_e32 v12, 63, v199
	s_waitcnt lgkmcnt(0)
	s_add_u32 s0, s10, s0
	v_cndmask_b32_e32 v3, v222, v3, vcc
	v_lshlrev_b32_e32 v10, 2, v3
	v_xor_b32_e32 v3, 32, v222
	v_cmp_lt_i32_e32 vcc, v3, v2
	v_readlane_b32 s6, v251, 9
	v_lshlrev_b32_e32 v4, 4, v12
	v_mov_b32_e32 v5, 0
	v_cndmask_b32_e32 v2, v222, v3, vcc
	s_addc_u32 s1, s11, s1
	v_readlane_b32 s7, v251, 10
	v_lshlrev_b32_e32 v11, 2, v2
	v_lshl_add_u64 v[2:3], s[0:1], 0, v[4:5]
	s_mov_b64 s[0:1], 0x800
	s_ashr_i32 s7, s6, 31
	v_lshl_add_u64 v[0:1], s[8:9], 0, v[4:5]
	v_lshl_add_u64 v[2:3], v[2:3], 0, s[0:1]
	s_lshl_b64 s[0:1], s[6:7], 12
	s_lshl_b64 s[2:3], s[2:3], 11
	v_readlane_b32 s8, v251, 5
	v_readlane_b32 s9, v251, 6
	s_add_u32 s2, s8, s2
	v_lshlrev_b32_e32 v4, 3, v12
	s_addc_u32 s3, s9, s3
	v_lshl_add_u64 v[4:5], s[2:3], 0, v[4:5]
	s_mov_b64 s[2:3], 0xa600400
	v_lshl_add_u64 v[4:5], v[4:5], 0, s[2:3]
	s_lshl_b64 s[2:3], s[6:7], 11
	v_mov_b32_e32 v12, 0x358637bd
	s_mov_b32 s5, 0x800000
	global_load_dwordx4 v[52:55], v[0:1], off
	global_load_dwordx4 v[56:59], v[0:1], off offset:1024
	global_load_dwordx4 v[60:63], v[0:1], off offset:2048
	global_load_dwordx4 v[64:67], v[0:1], off offset:3072
.LBB0_929:
	global_load_dwordx2 v[18:19], v[4:5], off offset:-1024
	global_load_dwordx2 v[20:21], v[4:5], off offset:-512
	global_load_dwordx2 v[22:23], v[4:5], off
	global_load_dwordx2 v[24:25], v[4:5], off offset:512
	s_add_i32 s4, s4, s6
	v_lshl_add_u64 v[4:5], v[4:5], 0, s[2:3]
	s_cmpk_lt_i32 s4, 0x4000
	s_waitcnt vmcnt(0)
	v_lshlrev_b32_e32 v26, 16, v18
	v_and_b32_e32 v27, 0xffff0000, v18
	v_lshlrev_b32_e32 v18, 16, v19
	v_and_b32_e32 v19, 0xffff0000, v19
	v_lshlrev_b32_e32 v29, 16, v21
	v_lshlrev_b32_e32 v28, 16, v20
	v_and_b32_e32 v21, 0xffff0000, v21
	v_and_b32_e32 v20, 0xffff0000, v20
	v_and_b32_e32 v31, 0xffff0000, v22
	v_lshlrev_b32_e32 v33, 16, v24
	v_and_b32_e32 v35, 0xffff0000, v24
	v_mul_f32_e32 v32, v19, v19
	v_mul_f32_e32 v34, v27, v27
	v_lshlrev_b32_e32 v30, 16, v22
	v_lshlrev_b32_e32 v22, 16, v23
	v_and_b32_e32 v23, 0xffff0000, v23
	v_pk_mul_f32 v[36:37], v[20:21], v[20:21]
	v_mov_b32_e32 v39, v33
	v_mul_f32_e32 v38, v31, v31
	v_pk_fma_f32 v[42:43], v[18:19], v[18:19], v[32:33] op_sel_hi:[1,1,0]
	v_pk_fma_f32 v[44:45], v[26:27], v[26:27], v[34:35] op_sel_hi:[1,1,0]
	v_lshlrev_b32_e32 v24, 16, v25
	v_and_b32_e32 v25, 0xffff0000, v25
	v_mul_f32_e32 v40, v23, v23
	v_pk_fma_f32 v[36:37], v[28:29], v[28:29], v[36:37]
	v_pk_fma_f32 v[46:47], v[30:31], v[30:31], v[38:39] op_sel_hi:[1,1,0]
	v_mov_b32_e32 v32, v44
	v_mov_b32_e32 v38, v42
	v_mul_f32_e32 v13, v35, v35
	v_mul_f32_e32 v48, v24, v24
	v_mul_f32_e32 v49, v25, v25
	v_pk_fma_f32 v[40:41], v[22:23], v[22:23], v[40:41] op_sel_hi:[1,1,0]
	v_pk_add_f32 v[42:43], v[44:45], v[42:43]
	v_pk_add_f32 v[36:37], v[36:37], v[36:37] op_sel:[0,1] op_sel_hi:[1,0]
	v_pk_mul_f32 v[38:39], v[32:33], v[38:39]
	v_mov_b32_e32 v47, v48
	v_mov_b32_e32 v41, v49
	v_mov_b32_e32 v37, v13
	v_mov_b32_e32 v43, v39
	v_pk_add_f32 v[40:41], v[46:47], v[40:41]
	v_pk_add_f32 v[36:37], v[42:43], v[36:37]
	v_mov_b32_e32 v34, v33
	v_pk_add_f32 v[36:37], v[36:37], v[40:41]
	s_nop 0
	v_add_f32_e32 v13, v36, v37
	ds_bpermute_b32 v32, v6, v13
	s_waitcnt lgkmcnt(0)
	v_add_f32_e32 v13, v13, v32
	ds_bpermute_b32 v32, v7, v13
	s_waitcnt lgkmcnt(0)
	v_add_f32_e32 v13, v13, v32
	ds_bpermute_b32 v32, v8, v13
	s_waitcnt lgkmcnt(0)
	v_add_f32_e32 v13, v13, v32
	ds_bpermute_b32 v32, v9, v13
	s_waitcnt lgkmcnt(0)
	v_add_f32_e32 v13, v13, v32
	ds_bpermute_b32 v32, v10, v13
	s_waitcnt lgkmcnt(0)
	v_add_f32_e32 v13, v13, v32
	ds_bpermute_b32 v32, v11, v13
	s_waitcnt lgkmcnt(0)
	v_add_f32_e32 v13, v13, v32
	v_fmamk_f32 v13, v13, 0x3a800000, v12
	v_mul_f32_e32 v32, 0x4b800000, v13
	v_cmp_gt_f32_e32 vcc, s5, v13
	s_nop 1
	v_cndmask_b32_e32 v13, v13, v32, vcc
	v_rsq_f32_e32 v13, v13
	s_nop 0
	v_mul_f32_e32 v32, 0x45800000, v13
	v_cndmask_b32_e32 v32, v13, v32, vcc
	v_pk_mul_f32 v[26:27], v[32:33], v[26:27] op_sel_hi:[0,1]
	v_pk_mul_f32 v[18:19], v[32:33], v[18:19] op_sel_hi:[0,1]
	v_pk_mul_f32 v[16:17], v[54:55], v[18:19]
	v_pk_mul_f32 v[14:15], v[52:53], v[26:27]
	global_store_dwordx4 v[2:3], v[14:17], off offset:-2048
	v_mov_b32_e32 v18, v29
	v_mov_b32_e32 v19, v21
	v_mov_b32_e32 v29, v20
	v_pk_mul_f32 v[18:19], v[32:33], v[18:19] op_sel_hi:[0,1]
	v_pk_mul_f32 v[20:21], v[32:33], v[28:29] op_sel_hi:[0,1]
	v_pk_mul_f32 v[68:69], v[56:57], v[20:21]
	v_pk_mul_f32 v[70:71], v[58:59], v[18:19]
	global_store_dwordx4 v[2:3], v[68:71], off offset:-1024
	v_pk_mul_f32 v[18:19], v[32:33], v[22:23] op_sel_hi:[0,1]
	v_pk_mul_f32 v[20:21], v[32:33], v[30:31] op_sel_hi:[0,1]
	v_pk_mul_f32 v[72:73], v[60:61], v[20:21]
	v_pk_mul_f32 v[74:75], v[62:63], v[18:19]
	global_store_dwordx4 v[2:3], v[72:75], off
	v_pk_mul_f32 v[18:19], v[32:33], v[24:25] op_sel_hi:[0,1]
	v_pk_mul_f32 v[20:21], v[32:33], v[34:35] op_sel_hi:[0,1]
	v_pk_mul_f32 v[76:77], v[64:65], v[20:21]
	v_pk_mul_f32 v[78:79], v[66:67], v[18:19]
	global_store_dwordx4 v[2:3], v[76:79], off offset:1024
	v_lshl_add_u64 v[2:3], v[2:3], 0, s[0:1]
	s_cbranch_scc1 .LBB0_929
